# P2 entry lambda block: xor1/xor2 wave-sum steps via DPP quad_perm, xor16/xor32 via permlane swaps
# baseline (speedup 1.0000x reference)
; __device__ __forceinline__ float wave_sum(float v) {
; #pragma unroll
;     for (int o = 1; o < 64; o <<= 1) v += __shfl_xor(v, o);
;     return v;
; __global__ void __launch_bounds__(NWAVES * 64, 2) mega_fwd(Args args) {
;     ...
;         const float d1 = wave_sum(lq1[lane] * lk1[lane]), d2 = wave_sum(lq2[lane] * lk2[lane]);
;         const float lam = expf(d1) - expf(d2) + 0.2f;
;         const att::SideJob SJ{w_out, w_up, w_dn, g_mlp, WOUT, WUP, WDN, vcu, 256, (G == 256) ? 36 : 0};
.Lp2_diff_entry:
	v_lshlrev_b32_e32 v1, 2, v194
	s_waitcnt vmcnt(0)
	v_mov_b32_e32 v2, v249
	v_mov_b32_e32 v3, v250
	v_mov_b32_e32 v4, v251
	v_mov_b32_e32 v5, v252
	v_mbcnt_lo_u32_b32 v1, -1, 0
	v_mbcnt_hi_u32_b32 v6, -1, v1
	v_and_b32_e32 v1, 64, v6
	v_xor_b32_e32 v7, 1, v6
	s_waitcnt vmcnt(0)
	v_add_u32_e32 v13, 64, v1
	v_cmp_lt_i32_e32 vcc, v7, v13
	v_xor_b32_e32 v8, 2, v6
	v_xor_b32_e32 v9, 4, v6
	v_cndmask_b32_e32 v1, v6, v7, vcc
	v_lshlrev_b32_e32 v1, 2, v1
	v_cmp_lt_i32_e32 vcc, v8, v13
	v_xor_b32_e32 v10, 8, v6
	v_xor_b32_e32 v11, 16, v6
	v_cndmask_b32_e32 v8, v6, v8, vcc
	v_lshlrev_b32_e32 v182, 2, v8
	v_cmp_lt_i32_e32 vcc, v9, v13
	v_xor_b32_e32 v12, 32, v6
	s_cmpk_gt_i32 s76, 0xff
	s_mov_b32 s1, 0
	v_mul_f32_e32 v7, v2, v3
	s_nop 1
	v_mov_b32_dpp v7, v7 quad_perm:[1,0,3,2] row_mask:0xf bank_mask:0xf
	v_mul_f32_e32 v14, v4, v5
	s_nop 1
	v_mov_b32_dpp v14, v14 quad_perm:[1,0,3,2] row_mask:0xf bank_mask:0xf
	s_waitcnt lgkmcnt(1)
	v_fmac_f32_e32 v7, v2, v3
	s_nop 1
	v_mov_b32_dpp v2, v7 quad_perm:[2,3,0,1] row_mask:0xf bank_mask:0xf
	s_waitcnt lgkmcnt(1)
	v_fmac_f32_e32 v14, v4, v5
	s_nop 1
	v_mov_b32_dpp v3, v14 quad_perm:[2,3,0,1] row_mask:0xf bank_mask:0xf
	v_cndmask_b32_e32 v4, v6, v9, vcc
	v_lshlrev_b32_e32 v183, 2, v4
	s_waitcnt lgkmcnt(1)
	v_add_f32_e32 v2, v7, v2
	ds_bpermute_b32 v4, v183, v2
	s_waitcnt lgkmcnt(1)
	v_add_f32_e32 v3, v14, v3
	ds_bpermute_b32 v5, v183, v3
	v_cmp_lt_i32_e32 vcc, v10, v13
	s_waitcnt lgkmcnt(1)
	v_add_f32_e32 v2, v2, v4
	v_cndmask_b32_e32 v7, v6, v10, vcc
	v_lshlrev_b32_e32 v184, 2, v7
	s_waitcnt lgkmcnt(0)
	v_add_f32_e32 v3, v3, v5
	ds_bpermute_b32 v4, v184, v2
	ds_bpermute_b32 v5, v184, v3
	v_cmp_lt_i32_e32 vcc, v11, v13
	s_waitcnt lgkmcnt(1)
	v_add_f32_e32 v2, v2, v4
	v_cndmask_b32_e32 v7, v6, v11, vcc
	v_lshlrev_b32_e32 v185, 2, v7
	s_waitcnt lgkmcnt(0)
	v_add_f32_e32 v3, v3, v5
	v_mov_b32_e32 v4, v2
	s_nop 1
	v_permlane16_swap_b32_e32 v4, v2
	v_mov_b32_e32 v5, v3
	s_nop 1
	v_permlane16_swap_b32_e32 v5, v3
	v_cmp_lt_i32_e32 vcc, v12, v13
	s_waitcnt lgkmcnt(1)
	v_add_f32_e32 v4, v2, v4
	v_cndmask_b32_e32 v6, v6, v12, vcc
	v_lshlrev_b32_e32 v6, 2, v6
	s_waitcnt lgkmcnt(0)
	v_add_f32_e32 v2, v3, v5
	v_mov_b32_e32 v5, v4
	s_nop 1
	v_permlane32_swap_b32_e32 v5, v4
	v_mov_b32_e32 v3, v2
	s_nop 1
	v_permlane32_swap_b32_e32 v3, v2
	s_cbranch_scc1 .LBB0_574
	s_waitcnt lgkmcnt(1)
	v_add_f32_e32 v4, v4, v5
	s_mov_b32 s0, 0x3fb8aa3b
	v_mul_f32_e32 v5, 0x3fb8aa3b, v4
	v_fma_f32 v6, v4, s0, -v5
	v_rndne_f32_e32 v7, v5
	v_fmac_f32_e32 v6, 0x32a5705f, v4
	v_sub_f32_e32 v5, v5, v7
	v_add_f32_e32 v5, v5, v6
	v_exp_f32_e32 v5, v5
	v_cvt_i32_f32_e32 v6, v7
	s_waitcnt lgkmcnt(0)
	v_add_f32_e32 v2, v2, v3
	s_mov_b32 s2, 0xc2ce8ed0
	v_cmp_ngt_f32_e32 vcc, s2, v4
	v_ldexp_f32 v3, v5, v6
	v_mul_f32_e32 v5, 0x3fb8aa3b, v2
	v_fma_f32 v6, v2, s0, -v5
	v_rndne_f32_e32 v7, v5
	v_fmac_f32_e32 v6, 0x32a5705f, v2
	v_sub_f32_e32 v5, v5, v7
	v_add_f32_e32 v5, v5, v6
	v_exp_f32_e32 v5, v5
	v_cvt_i32_f32_e32 v6, v7
	s_mov_b32 s3, 0x42b17218
	v_cndmask_b32_e32 v3, 0, v3, vcc
	v_mov_b32_e32 v7, 0x7f800000
	v_cmp_nlt_f32_e32 vcc, s3, v4
	v_readlane_b32 s6, v242, 12
	v_ldexp_f32 v4, v5, v6
	v_cndmask_b32_e32 v3, v7, v3, vcc
	v_cmp_ngt_f32_e32 vcc, s2, v2
	v_readlane_b32 s7, v242, 13
	v_mov_b32_e32 v147, 0
	v_cndmask_b32_e32 v4, 0, v4, vcc
	v_cmp_nlt_f32_e32 vcc, s3, v2
	s_and_b64 s[2:3], s[6:7], exec
	s_cselect_b32 s3, 36, 0
	s_add_u32 s12, s70, 0xe014100
	s_addc_u32 s13, s71, 0
	s_and_b64 s[4:5], s[6:7], exec
	s_cselect_b32 s42, 0x100, 0
	s_lshl_b32 s0, s76, 6
	s_and_b32 s43, s0, 0x7c0
	v_cndmask_b32_e32 v2, v7, v4, vcc
	s_add_u32 s44, s70, 0x4002000
	v_sub_f32_e32 v2, v3, v2
	s_addc_u32 s45, s71, 0
	v_add_f32_e32 v186, 0x3e4ccccd, v2
	s_add_u32 s46, s70, 0x500c000
	v_cndmask_b32_e64 v2, 0, 1, s[6:7]
	s_addc_u32 s47, s71, 0
	v_cmp_ne_u32_e64 s[4:5], 1, v2
	s_mov_b64 s[14:15], 0x400
	s_mov_b64 s[16:17], 0x4000
	s_add_i32 s48, 0, 0x1c800
	s_mov_b64 s[18:19], 0x8000
	s_mov_b32 s49, 0x41000000
	s_movk_i32 s78, 0x1000
	v_mov_b32_e32 v187, 0x3727c5ac
	s_mov_b32 s79, s76
	s_branch .LBB0_399
